# dilated attention: the K/V/Q staging loads (read about once) carry the nt cache hint
# speedup vs baseline: 1.0151x; 1.0151x over previous
.LBB0_679:
	s_add_i32 s2, s92, -6
	s_lshr_b32 s8, s2, 1
	s_cmp_gt_u32 s2, 1
	s_cselect_b64 s[24:25], -1, 0
	s_cmp_eq_u32 s8, 1
	s_cselect_b64 s[4:5], -1, 0
	s_and_b64 s[0:1], s[4:5], exec
	s_cselect_b32 s3, 4, 16
	s_cselect_b32 s9, 8, 2
	s_cselect_b32 s10, 8, 10
	s_cmp_lt_u32 s2, 2
	s_cselect_b64 s[6:7], -1, 0
	s_and_b64 s[0:1], s[6:7], exec
	s_cselect_b32 s41, 32, s9
	s_cselect_b32 s9, 6, s10
	v_readlane_b32 s10, v254, 21
	v_readlane_b32 s11, v254, 22
	s_cselect_b32 s40, 1, s3
	s_load_dwordx4 s[0:3], s[10:11], 0x40
	s_lshl_b32 s88, s8, 6
	s_lshl_b32 s70, s41, s9
	s_lshl_b64 s[8:9], s[88:89], 2
	v_and_b32_e32 v6, 63, v170
	s_waitcnt lgkmcnt(0)
	s_add_u32 s0, s0, s8
	s_addc_u32 s1, s1, s9
	s_add_u32 s2, s2, s8
	v_lshlrev_b32_e32 v7, 2, v6
	global_load_dword v1, v7, s[0:1]
	s_addc_u32 s3, s3, s9
	global_load_dword v2, v7, s[2:3]
	v_and_b32_e32 v3, 64, v224
	v_xor_b32_e32 v4, 32, v224
	v_add_u32_e32 v3, 64, v3
	v_xor_b32_e32 v5, 16, v224
	v_cmp_lt_i32_e32 vcc, v4, v3
	v_xor_b32_e32 v8, 8, v224
	v_xor_b32_e32 v9, 4, v224
	v_cndmask_b32_e32 v4, v224, v4, vcc
	v_cmp_lt_i32_e32 vcc, v5, v3
	v_lshlrev_b32_e32 v145, 2, v4
	v_xor_b32_e32 v10, 2, v224
	v_cndmask_b32_e32 v5, v224, v5, vcc
	v_lshlrev_b32_e32 v4, 2, v5
	v_cmp_lt_i32_e32 vcc, v8, v3
	v_xor_b32_e32 v11, 1, v224
	s_cmp_lt_i32 s81, s70
	s_cselect_b64 s[8:9], -1, 0
	s_cmp_ge_i32 s81, s70
	s_waitcnt vmcnt(0)
	v_and_b32_e32 v5, 0x7fffffff, v1
	ds_bpermute_b32 v5, v145, v5
	v_and_b32_e32 v12, 0x7fffffff, v2
	ds_bpermute_b32 v12, v145, v12
	v_max_f32_e64 v1, |v1|, |v1|
	v_max_f32_e64 v2, |v2|, |v2|
	s_waitcnt lgkmcnt(1)
	v_max_f32_e32 v5, v5, v5
	v_max_f32_e32 v1, v1, v5
	s_waitcnt lgkmcnt(0)
	v_max_f32_e32 v5, v12, v12
	ds_bpermute_b32 v12, v4, v1
	v_max_f32_e32 v2, v2, v5
	ds_bpermute_b32 v4, v4, v2
	v_cndmask_b32_e32 v5, v224, v8, vcc
	v_lshlrev_b32_e32 v5, 2, v5
	s_waitcnt lgkmcnt(1)
	v_max_f32_e32 v8, v12, v12
	v_max_f32_e32 v1, v1, v8
	s_waitcnt lgkmcnt(0)
	v_max_f32_e32 v4, v4, v4
	ds_bpermute_b32 v8, v5, v1
	v_max_f32_e32 v2, v2, v4
	ds_bpermute_b32 v4, v5, v2
	v_cmp_lt_i32_e32 vcc, v9, v3
	s_waitcnt lgkmcnt(1)
	v_max_f32_e32 v8, v8, v8
	v_cndmask_b32_e32 v5, v224, v9, vcc
	v_lshlrev_b32_e32 v5, 2, v5
	v_max_f32_e32 v1, v1, v8
	s_waitcnt lgkmcnt(0)
	v_max_f32_e32 v4, v4, v4
	ds_bpermute_b32 v8, v5, v1
	v_max_f32_e32 v2, v2, v4
	ds_bpermute_b32 v4, v5, v2
	v_cmp_lt_i32_e32 vcc, v10, v3
	s_waitcnt lgkmcnt(1)
	v_max_f32_e32 v8, v8, v8
	v_cndmask_b32_e32 v5, v224, v10, vcc
	v_lshlrev_b32_e32 v5, 2, v5
	v_max_f32_e32 v1, v1, v8
	s_waitcnt lgkmcnt(0)
	v_max_f32_e32 v4, v4, v4
	ds_bpermute_b32 v8, v5, v1
	v_max_f32_e32 v2, v2, v4
	ds_bpermute_b32 v4, v5, v2
	v_cmp_lt_i32_e32 vcc, v11, v3
	s_waitcnt lgkmcnt(1)
	v_max_f32_e32 v5, v8, v8
	v_cndmask_b32_e32 v3, v224, v11, vcc
	v_max_f32_e32 v9, v1, v5
	s_waitcnt lgkmcnt(0)
	v_max_f32_e32 v1, v4, v4
	v_lshlrev_b32_e32 v3, 2, v3
	v_max_f32_e32 v8, v2, v1
	ds_bpermute_b32 v11, v3, v9
	ds_bpermute_b32 v10, v3, v8
	s_cbranch_scc1 .LBB0_713
	v_cvt_f32_ubyte0_e32 v1, s41
	v_rcp_iflag_f32_e32 v1, v1
	s_sub_i32 s2, 0, s41
	s_abs_i32 s1, s81
	s_ashr_i32 s0, s81, 31
	v_mul_f32_e32 v1, 0x4f7ffffe, v1
	v_cvt_u32_f32_e32 v1, v1
	v_mov_b32_e32 v3, 0xfffffe80
	v_mov_b32_e32 v66, v0
	v_mov_b32_e32 v67, v0
	v_readfirstlane_b32 s3, v1
	s_mul_i32 s2, s2, s3
	s_mul_hi_u32 s2, s3, s2
	s_add_i32 s3, s3, s2
	s_mul_hi_u32 s2, s1, s3
	s_mul_i32 s3, s2, s41
	s_sub_i32 s1, s1, s3
	s_add_i32 s10, s2, 1
	s_sub_i32 s3, s1, s41
	s_cmp_ge_u32 s1, s41
	s_cselect_b32 s2, s10, s2
	v_cvt_f32_ubyte0_e32 v1, s40
	s_cselect_b32 s1, s3, s1
	s_add_i32 s3, s2, 1
	v_rcp_iflag_f32_e32 v1, v1
	s_cmp_ge_u32 s1, s41
	s_cselect_b32 s1, s3, s2
	s_xor_b32 s1, s1, s0
	s_sub_i32 s0, s1, s0
	v_mul_f32_e32 v1, 0x4f7ffffe, v1
	s_ashr_i32 s2, s0, 31
	v_cvt_u32_f32_e32 v1, v1
	s_lshr_b32 s2, s2, 28
	s_add_i32 s2, s0, s2
	s_and_b32 s10, s2, 0x3fffff0
	s_sub_i32 s12, s0, s10
	s_sub_i32 s10, 0, s40
	v_readfirstlane_b32 s11, v1
	s_mul_i32 s10, s10, s11
	s_ashr_i32 s3, s2, 4
	s_mul_hi_u32 s10, s11, s10
	s_mul_i32 s1, s0, s41
	s_ashr_i32 s0, s2, 31
	s_abs_i32 s2, s3
	s_add_i32 s11, s11, s10
	s_mul_hi_u32 s10, s2, s11
	s_mul_i32 s11, s10, s40
	s_sub_i32 s2, s2, s11
	s_sub_i32 s1, s81, s1
	s_add_i32 s11, s10, 1
	s_sub_i32 s13, s2, s40
	s_cmp_ge_u32 s2, s40
	s_cselect_b32 s10, s11, s10
	s_cselect_b32 s2, s13, s2
	s_add_i32 s11, s10, 1
	s_cmp_ge_u32 s2, s40
	s_cselect_b32 s2, s11, s10
	s_xor_b32 s2, s2, s0
	s_sub_i32 s0, s2, s0
	s_mul_i32 s2, s0, s40
	s_sub_i32 s2, s3, s2
	s_lshl_b32 s15, s1, 8
	s_ashr_i32 s1, s0, 31
	v_ashrrev_i32_e32 v1, 3, v170
	s_add_i32 s16, s15, 0xffffff80
	s_lshl_b64 s[0:1], s[0:1], 13
	s_ashr_i32 s3, s2, 31
	v_add_u32_e32 v2, 0xfffffe80, v1
	s_add_u32 s10, s0, s2
	v_cmp_gt_u32_e32 vcc, s63, v2
	v_mov_b32_e32 v2, 0xfffffd00
	s_addc_u32 s11, s1, s3
	v_cndmask_b32_e32 v2, v2, v3, vcc
	v_cmp_lt_i32_e64 s[0:1], s61, v1
	v_mov_b32_e32 v3, s15
	v_mov_b32_e32 v4, s16
	v_cmp_gt_i32_e64 s[2:3], s62, v1
	v_cndmask_b32_e64 v2, 0, v2, s[0:1]
	v_mov_b32_e32 v64, v0
	v_cndmask_b32_e64 v3, v3, v4, s[2:3]
	v_add3_u32 v2, v2, v1, v3
	v_mov_b32_e32 v65, v0
	v_mov_b64_e32 v[70:71], v[66:67]
	s_lshl_b32 s14, s12, 6
	v_cmp_lt_i32_e64 s[2:3], -1, v2
	v_mov_b64_e32 v[68:69], v[64:65]
	s_and_saveexec_b64 s[12:13], s[2:3]
	s_cbranch_execz .LBB0_682
	s_and_b64 s[2:3], s[4:5], exec
	s_cselect_b32 s17, 2, 4
	s_and_b64 s[2:3], s[6:7], exec
	v_cndmask_b32_e32 v1, 0, v229, vcc
	v_mov_b32_e32 v3, v0
	s_cselect_b32 s2, 0, s17
	v_cndmask_b32_e64 v1, v230, v1, s[0:1]
	v_readlane_b32 s0, v254, 27
	v_lshlrev_b64 v[2:3], s2, v[2:3]
	v_readlane_b32 s1, v254, 28
	v_lshl_add_u64 v[2:3], v[2:3], 0, s[10:11]
	v_add_u32_e32 v1, s14, v1
	v_lshlrev_b32_e32 v4, 3, v170
	v_mov_b64_e32 v[12:13], s[0:1]
	v_and_or_b32 v4, v4, 56, v1
	v_mad_u64_u32 v[12:13], s[0:1], v2, s82, v[12:13]
	v_mad_i32_i24 v13, v3, s82, v13
	v_ashrrev_i32_e32 v5, 31, v4
	v_lshl_add_u64 v[2:3], v[4:5], 1, v[12:13]
	global_load_dwordx4 v[68:71], v[2:3], off nt
.LBB0_682:
	s_or_b64 exec, exec, s[12:13]
	v_add_u32_e32 v1, 0x200, v170
	v_ashrrev_i32_e32 v1, 3, v1
	v_add_u32_e32 v2, 0xfffffe80, v1
	v_cmp_gt_u32_e32 vcc, s63, v2
	v_mov_b32_e32 v2, 0xfffffd00
	v_mov_b32_e32 v3, 0xfffffe80
	v_cndmask_b32_e32 v2, v2, v3, vcc
	v_cmp_lt_i32_e64 s[0:1], s61, v1
	v_mov_b32_e32 v3, s15
	v_mov_b32_e32 v4, s16
	v_cmp_gt_i32_e64 s[2:3], s62, v1
	v_cndmask_b32_e64 v2, 0, v2, s[0:1]
	s_nop 0
	v_cndmask_b32_e64 v3, v3, v4, s[2:3]
	v_add3_u32 v2, v2, v1, v3
	v_cmp_lt_i32_e64 s[2:3], -1, v2
	s_and_saveexec_b64 s[12:13], s[2:3]
	s_cbranch_execz .LBB0_684
	s_and_b64 s[2:3], s[4:5], exec
	s_cselect_b32 s17, 2, 4
	s_and_b64 s[2:3], s[6:7], exec
	v_cndmask_b32_e32 v1, 0, v229, vcc
	v_mov_b32_e32 v3, v0
	s_cselect_b32 s2, 0, s17
	v_cndmask_b32_e64 v1, v230, v1, s[0:1]
	v_readlane_b32 s0, v254, 27
	v_lshlrev_b64 v[2:3], s2, v[2:3]
	v_readlane_b32 s1, v254, 28
	v_lshl_add_u64 v[2:3], v[2:3], 0, s[10:11]
	v_add_u32_e32 v1, s14, v1
	v_lshlrev_b32_e32 v4, 3, v170
	v_mov_b64_e32 v[12:13], s[0:1]
	v_and_or_b32 v4, v4, 56, v1
	v_mad_u64_u32 v[12:13], s[0:1], v2, s82, v[12:13]
	v_mad_i32_i24 v13, v3, s82, v13
	v_ashrrev_i32_e32 v5, 31, v4
	v_lshl_add_u64 v[2:3], v[4:5], 1, v[12:13]
	global_load_dwordx4 v[64:67], v[2:3], off nt
.LBB0_684:
	s_or_b64 exec, exec, s[12:13]
	v_add_u32_e32 v1, 0x400, v170
	v_ashrrev_i32_e32 v1, 3, v1
	v_add_u32_e32 v2, 0xfffffe80, v1
	v_cmp_gt_u32_e32 vcc, s63, v2
	v_mov_b32_e32 v2, 0xfffffd00
	v_mov_b32_e32 v3, 0xfffffe80
	v_cndmask_b32_e32 v2, v2, v3, vcc
	v_cmp_lt_i32_e64 s[0:1], s61, v1
	v_mov_b32_e32 v3, s15
	v_mov_b32_e32 v4, s16
	v_cmp_gt_i32_e64 s[2:3], s62, v1
	v_cndmask_b32_e64 v2, 0, v2, s[0:1]
	s_nop 0
	v_cndmask_b32_e64 v3, v3, v4, s[2:3]
	v_add3_u32 v4, v2, v1, v3
	v_mov_b32_e32 v2, v0
	v_mov_b32_e32 v3, v0
	v_mov_b32_e32 v1, v0
	v_mov_b64_e32 v[74:75], v[2:3]
	v_cmp_lt_i32_e64 s[2:3], -1, v4
	v_mov_b64_e32 v[72:73], v[0:1]
	s_and_saveexec_b64 s[12:13], s[2:3]
	s_cbranch_execz .LBB0_686
	s_and_b64 s[2:3], s[4:5], exec
	s_cselect_b32 s17, 2, 4
	s_and_b64 s[2:3], s[6:7], exec
	v_cndmask_b32_e32 v12, 0, v229, vcc
	v_mov_b32_e32 v5, v0
	s_cselect_b32 s2, 0, s17
	v_cndmask_b32_e64 v12, v230, v12, s[0:1]
	v_readlane_b32 s0, v254, 27
	v_lshlrev_b64 v[4:5], s2, v[4:5]
	v_readlane_b32 s1, v254, 28
	v_lshl_add_u64 v[4:5], v[4:5], 0, s[10:11]
	v_add_u32_e32 v12, s14, v12
	v_lshlrev_b32_e32 v13, 3, v170
	v_mov_b64_e32 v[14:15], s[0:1]
	v_and_or_b32 v12, v13, 56, v12
	v_mad_u64_u32 v[14:15], s[0:1], v4, s82, v[14:15]
	v_mad_i32_i24 v15, v5, s82, v15
	v_ashrrev_i32_e32 v13, 31, v12
	v_lshl_add_u64 v[4:5], v[12:13], 1, v[14:15]
	global_load_dwordx4 v[72:75], v[4:5], off nt
.LBB0_686:
	s_or_b64 exec, exec, s[12:13]
	v_add_u32_e32 v4, 0x600, v170
	v_ashrrev_i32_e32 v4, 3, v4
	v_add_u32_e32 v5, 0xfffffe80, v4
	v_cmp_gt_u32_e32 vcc, s63, v5
	v_mov_b32_e32 v5, 0xfffffd00
	v_mov_b32_e32 v12, 0xfffffe80
	v_cndmask_b32_e32 v5, v5, v12, vcc
	v_cmp_lt_i32_e64 s[0:1], s61, v4
	v_mov_b32_e32 v12, s15
	v_mov_b32_e32 v13, s16
	v_cmp_gt_i32_e64 s[2:3], s62, v4
	v_cndmask_b32_e64 v5, 0, v5, s[0:1]
	v_mov_b64_e32 v[78:79], v[2:3]
	v_cndmask_b32_e64 v12, v12, v13, s[2:3]
	v_add3_u32 v4, v5, v4, v12
	v_cmp_lt_i32_e64 s[2:3], -1, v4
	v_mov_b64_e32 v[76:77], v[0:1]
	s_and_saveexec_b64 s[12:13], s[2:3]
	s_cbranch_execz .LBB0_688
	s_and_b64 s[2:3], s[4:5], exec
	s_cselect_b32 s17, 2, 4
	s_and_b64 s[2:3], s[6:7], exec
	v_cndmask_b32_e32 v1, 0, v229, vcc
	v_mov_b32_e32 v5, v0
	s_cselect_b32 s2, 0, s17
	v_cndmask_b32_e64 v1, v230, v1, s[0:1]
	v_readlane_b32 s0, v254, 27
	v_lshlrev_b64 v[2:3], s2, v[4:5]
	v_readlane_b32 s1, v254, 28
	v_lshl_add_u64 v[2:3], v[2:3], 0, s[10:11]
	v_add_u32_e32 v1, s14, v1
	v_lshlrev_b32_e32 v4, 3, v170
	v_mov_b64_e32 v[12:13], s[0:1]
	v_and_or_b32 v4, v4, 56, v1
	v_mad_u64_u32 v[12:13], s[0:1], v2, s82, v[12:13]
	v_mad_i32_i24 v13, v3, s82, v13
	v_ashrrev_i32_e32 v5, 31, v4
	v_lshl_add_u64 v[2:3], v[4:5], 1, v[12:13]
	global_load_dwordx4 v[76:79], v[2:3], off nt
.LBB0_688:
	s_or_b64 exec, exec, s[12:13]
	v_add_u32_e32 v1, 0x800, v170
	v_ashrrev_i32_e32 v1, 3, v1
	v_add_u32_e32 v2, 0xfffffe80, v1
	v_cmp_gt_u32_e32 vcc, s63, v2
	v_mov_b32_e32 v2, 0xfffffd00
	v_mov_b32_e32 v3, 0xfffffe80
	v_cndmask_b32_e32 v2, v2, v3, vcc
	v_cmp_lt_i32_e64 s[0:1], s61, v1
	v_mov_b32_e32 v3, s15
	v_mov_b32_e32 v4, s16
	v_cmp_gt_i32_e64 s[2:3], s62, v1
	v_cndmask_b32_e64 v2, 0, v2, s[0:1]
	s_nop 0
	v_cndmask_b32_e64 v3, v3, v4, s[2:3]
	v_add3_u32 v4, v2, v1, v3
	v_mov_b32_e32 v2, v0
	v_mov_b32_e32 v3, v0
	v_mov_b32_e32 v1, v0
	v_mov_b64_e32 v[82:83], v[2:3]
	v_cmp_lt_i32_e64 s[2:3], -1, v4
	v_mov_b64_e32 v[80:81], v[0:1]
	s_and_saveexec_b64 s[12:13], s[2:3]
	s_cbranch_execz .LBB0_690
	s_and_b64 s[2:3], s[4:5], exec
	s_cselect_b32 s17, 2, 4
	s_and_b64 s[2:3], s[6:7], exec
	v_cndmask_b32_e32 v12, 0, v229, vcc
	v_mov_b32_e32 v5, v0
	s_cselect_b32 s2, 0, s17
	v_cndmask_b32_e64 v12, v230, v12, s[0:1]
	v_readlane_b32 s0, v254, 27
	v_lshlrev_b64 v[4:5], s2, v[4:5]
	v_readlane_b32 s1, v254, 28
	v_lshl_add_u64 v[4:5], v[4:5], 0, s[10:11]
	v_add_u32_e32 v12, s14, v12
	v_lshlrev_b32_e32 v13, 3, v170
	v_mov_b64_e32 v[14:15], s[0:1]
	v_and_or_b32 v12, v13, 56, v12
	v_mad_u64_u32 v[14:15], s[0:1], v4, s82, v[14:15]
	v_mad_i32_i24 v15, v5, s82, v15
	v_ashrrev_i32_e32 v13, 31, v12
	v_lshl_add_u64 v[4:5], v[12:13], 1, v[14:15]
	global_load_dwordx4 v[80:83], v[4:5], off nt
.LBB0_690:
	s_or_b64 exec, exec, s[12:13]
	v_add_u32_e32 v4, 0xa00, v170
	v_ashrrev_i32_e32 v4, 3, v4
	v_add_u32_e32 v5, 0xfffffe80, v4
	v_cmp_gt_u32_e32 vcc, s63, v5
	v_mov_b32_e32 v5, 0xfffffd00
	v_mov_b32_e32 v12, 0xfffffe80
	v_cndmask_b32_e32 v5, v5, v12, vcc
	v_cmp_lt_i32_e64 s[0:1], s61, v4
	v_mov_b32_e32 v12, s15
	v_mov_b32_e32 v13, s16
	v_cmp_gt_i32_e64 s[2:3], s62, v4
	v_cndmask_b32_e64 v5, 0, v5, s[0:1]
	v_mov_b64_e32 v[86:87], v[2:3]
	v_cndmask_b32_e64 v12, v12, v13, s[2:3]
	v_add3_u32 v4, v5, v4, v12
	v_cmp_lt_i32_e64 s[2:3], -1, v4
	v_mov_b64_e32 v[84:85], v[0:1]
	s_and_saveexec_b64 s[12:13], s[2:3]
	s_cbranch_execz .LBB0_692
	s_and_b64 s[2:3], s[4:5], exec
	s_cselect_b32 s17, 2, 4
	s_and_b64 s[2:3], s[6:7], exec
	v_cndmask_b32_e32 v1, 0, v229, vcc
	v_mov_b32_e32 v5, v0
	s_cselect_b32 s2, 0, s17
	v_cndmask_b32_e64 v1, v230, v1, s[0:1]
	v_readlane_b32 s0, v254, 27
	v_lshlrev_b64 v[2:3], s2, v[4:5]
	v_readlane_b32 s1, v254, 28
	v_lshl_add_u64 v[2:3], v[2:3], 0, s[10:11]
	v_add_u32_e32 v1, s14, v1
	v_lshlrev_b32_e32 v4, 3, v170
	v_mov_b64_e32 v[12:13], s[0:1]
	v_and_or_b32 v4, v4, 56, v1
	v_mad_u64_u32 v[12:13], s[0:1], v2, s82, v[12:13]
	v_mad_i32_i24 v13, v3, s82, v13
	v_ashrrev_i32_e32 v5, 31, v4
	v_lshl_add_u64 v[2:3], v[4:5], 1, v[12:13]
	global_load_dwordx4 v[84:87], v[2:3], off nt
.LBB0_692:
	s_or_b64 exec, exec, s[12:13]
	v_add_u32_e32 v1, 0xc00, v170
	v_ashrrev_i32_e32 v1, 3, v1
	v_add_u32_e32 v2, 0xfffffe80, v1
	v_cmp_gt_u32_e32 vcc, s63, v2
	v_mov_b32_e32 v2, 0xfffffd00
	v_mov_b32_e32 v3, 0xfffffe80
	v_cndmask_b32_e32 v2, v2, v3, vcc
	v_cmp_lt_i32_e64 s[0:1], s61, v1
	v_mov_b32_e32 v3, s15
	v_mov_b32_e32 v4, s16
	v_cmp_gt_i32_e64 s[2:3], s62, v1
	v_cndmask_b32_e64 v2, 0, v2, s[0:1]
	s_nop 0
	v_cndmask_b32_e64 v3, v3, v4, s[2:3]
	v_add3_u32 v4, v2, v1, v3
	v_mov_b32_e32 v2, v0
	v_mov_b32_e32 v3, v0
	v_mov_b32_e32 v1, v0
	v_mov_b64_e32 v[90:91], v[2:3]
	v_cmp_lt_i32_e64 s[2:3], -1, v4
	v_mov_b64_e32 v[88:89], v[0:1]
	s_and_saveexec_b64 s[12:13], s[2:3]
	s_cbranch_execz .LBB0_694
	s_and_b64 s[2:3], s[4:5], exec
	s_cselect_b32 s17, 2, 4
	s_and_b64 s[2:3], s[6:7], exec
	v_cndmask_b32_e32 v12, 0, v229, vcc
	v_mov_b32_e32 v5, v0
	s_cselect_b32 s2, 0, s17
	v_cndmask_b32_e64 v12, v230, v12, s[0:1]
	v_readlane_b32 s0, v254, 27
	v_lshlrev_b64 v[4:5], s2, v[4:5]
	v_readlane_b32 s1, v254, 28
	v_lshl_add_u64 v[4:5], v[4:5], 0, s[10:11]
	v_add_u32_e32 v12, s14, v12
	v_lshlrev_b32_e32 v13, 3, v170
	v_mov_b64_e32 v[14:15], s[0:1]
	v_and_or_b32 v12, v13, 56, v12
	v_mad_u64_u32 v[14:15], s[0:1], v4, s82, v[14:15]
	v_mad_i32_i24 v15, v5, s82, v15
	v_ashrrev_i32_e32 v13, 31, v12
	v_lshl_add_u64 v[4:5], v[12:13], 1, v[14:15]
	global_load_dwordx4 v[88:91], v[4:5], off nt
.LBB0_694:
	s_or_b64 exec, exec, s[12:13]
	v_add_u32_e32 v4, 0xe00, v170
	v_ashrrev_i32_e32 v4, 3, v4
	v_add_u32_e32 v5, 0xfffffe80, v4
	v_cmp_gt_u32_e32 vcc, s63, v5
	v_mov_b32_e32 v5, 0xfffffd00
	v_mov_b32_e32 v12, 0xfffffe80
	v_cndmask_b32_e32 v5, v5, v12, vcc
	v_cmp_lt_i32_e64 s[0:1], s61, v4
	v_mov_b32_e32 v12, s15
	v_mov_b32_e32 v13, s16
	v_cmp_gt_i32_e64 s[2:3], s62, v4
	v_cndmask_b32_e64 v5, 0, v5, s[0:1]
	v_mov_b64_e32 v[94:95], v[2:3]
	v_cndmask_b32_e64 v12, v12, v13, s[2:3]
	v_add3_u32 v4, v5, v4, v12
	v_cmp_lt_i32_e64 s[2:3], -1, v4
	v_mov_b64_e32 v[92:93], v[0:1]
	s_and_saveexec_b64 s[12:13], s[2:3]
	s_cbranch_execz .LBB0_696
	s_and_b64 s[2:3], s[4:5], exec
	s_cselect_b32 s17, 2, 4
	s_and_b64 s[2:3], s[6:7], exec
	v_cndmask_b32_e32 v1, 0, v229, vcc
	v_mov_b32_e32 v5, v0
	s_cselect_b32 s2, 0, s17
	v_cndmask_b32_e64 v1, v230, v1, s[0:1]
	v_readlane_b32 s0, v254, 27
	v_lshlrev_b64 v[2:3], s2, v[4:5]
	v_readlane_b32 s1, v254, 28
	v_lshl_add_u64 v[2:3], v[2:3], 0, s[10:11]
	v_add_u32_e32 v1, s14, v1
	v_lshlrev_b32_e32 v4, 3, v170
	v_mov_b64_e32 v[12:13], s[0:1]
	v_and_or_b32 v4, v4, 56, v1
	v_mad_u64_u32 v[12:13], s[0:1], v2, s82, v[12:13]
	v_mad_i32_i24 v13, v3, s82, v13
	v_ashrrev_i32_e32 v5, 31, v4
	v_lshl_add_u64 v[2:3], v[4:5], 1, v[12:13]
	global_load_dwordx4 v[92:95], v[2:3], off nt
.LBB0_696:
	s_or_b64 exec, exec, s[12:13]
	v_add_u32_e32 v1, 0x1000, v170
	v_ashrrev_i32_e32 v1, 3, v1
	v_add_u32_e32 v2, 0xfffffe80, v1
	v_cmp_gt_u32_e32 vcc, s63, v2
	v_mov_b32_e32 v2, 0xfffffd00
	v_mov_b32_e32 v3, 0xfffffe80
	v_cndmask_b32_e32 v2, v2, v3, vcc
	v_cmp_lt_i32_e64 s[0:1], s61, v1
	v_mov_b32_e32 v3, s15
	v_mov_b32_e32 v4, s16
	v_cmp_gt_i32_e64 s[2:3], s62, v1
	v_cndmask_b32_e64 v2, 0, v2, s[0:1]
	s_nop 0
	v_cndmask_b32_e64 v3, v3, v4, s[2:3]
	v_add3_u32 v4, v2, v1, v3
	v_mov_b32_e32 v2, v0
	v_mov_b32_e32 v3, v0
	v_mov_b32_e32 v1, v0
	v_mov_b64_e32 v[98:99], v[2:3]
	v_cmp_lt_i32_e64 s[2:3], -1, v4
	v_mov_b64_e32 v[96:97], v[0:1]
	s_and_saveexec_b64 s[12:13], s[2:3]
	s_cbranch_execz .LBB0_698
	s_and_b64 s[2:3], s[4:5], exec
	s_cselect_b32 s17, 2, 4
	s_and_b64 s[2:3], s[6:7], exec
	v_cndmask_b32_e32 v12, 0, v229, vcc
	v_mov_b32_e32 v5, v0
	s_cselect_b32 s2, 0, s17
	v_cndmask_b32_e64 v12, v230, v12, s[0:1]
	v_readlane_b32 s0, v254, 27
	v_lshlrev_b64 v[4:5], s2, v[4:5]
	v_readlane_b32 s1, v254, 28
	v_lshl_add_u64 v[4:5], v[4:5], 0, s[10:11]
	v_add_u32_e32 v12, s14, v12
	v_lshlrev_b32_e32 v13, 3, v170
	v_mov_b64_e32 v[14:15], s[0:1]
	v_and_or_b32 v12, v13, 56, v12
	v_mad_u64_u32 v[14:15], s[0:1], v4, s82, v[14:15]
	v_mad_i32_i24 v15, v5, s82, v15
	v_ashrrev_i32_e32 v13, 31, v12
	v_lshl_add_u64 v[4:5], v[12:13], 1, v[14:15]
	global_load_dwordx4 v[96:99], v[4:5], off nt
.LBB0_698:
	s_or_b64 exec, exec, s[12:13]
	v_add_u32_e32 v4, 0x1200, v170
	v_ashrrev_i32_e32 v4, 3, v4
	v_add_u32_e32 v5, 0xfffffe80, v4
	v_cmp_gt_u32_e32 vcc, s63, v5
	v_mov_b32_e32 v5, 0xfffffd00
	v_mov_b32_e32 v12, 0xfffffe80
	v_cndmask_b32_e32 v5, v5, v12, vcc
	v_cmp_lt_i32_e64 s[0:1], s61, v4
	v_mov_b32_e32 v12, s15
	v_mov_b32_e32 v13, s16
	v_cmp_gt_i32_e64 s[2:3], s62, v4
	v_cndmask_b32_e64 v5, 0, v5, s[0:1]
	v_mov_b64_e32 v[102:103], v[2:3]
	v_cndmask_b32_e64 v12, v12, v13, s[2:3]
	v_add3_u32 v4, v5, v4, v12
	v_cmp_lt_i32_e64 s[2:3], -1, v4
	v_mov_b64_e32 v[100:101], v[0:1]
	s_and_saveexec_b64 s[12:13], s[2:3]
	s_cbranch_execz .LBB0_700
	s_and_b64 s[2:3], s[4:5], exec
	s_cselect_b32 s17, 2, 4
	s_and_b64 s[2:3], s[6:7], exec
	v_cndmask_b32_e32 v1, 0, v229, vcc
	v_mov_b32_e32 v5, v0
	s_cselect_b32 s2, 0, s17
	v_cndmask_b32_e64 v1, v230, v1, s[0:1]
	v_readlane_b32 s0, v254, 27
	v_lshlrev_b64 v[2:3], s2, v[4:5]
	v_readlane_b32 s1, v254, 28
	v_lshl_add_u64 v[2:3], v[2:3], 0, s[10:11]
	v_add_u32_e32 v1, s14, v1
	v_lshlrev_b32_e32 v4, 3, v170
	v_mov_b64_e32 v[12:13], s[0:1]
	v_and_or_b32 v4, v4, 56, v1
	v_mad_u64_u32 v[12:13], s[0:1], v2, s82, v[12:13]
	v_mad_i32_i24 v13, v3, s82, v13
	v_ashrrev_i32_e32 v5, 31, v4
	v_lshl_add_u64 v[2:3], v[4:5], 1, v[12:13]
	global_load_dwordx4 v[100:103], v[2:3], off nt
.LBB0_700:
	s_or_b64 exec, exec, s[12:13]
	v_add_u32_e32 v1, 0x1400, v170
	v_ashrrev_i32_e32 v1, 3, v1
	v_add_u32_e32 v2, 0xfffffe80, v1
	v_cmp_gt_u32_e32 vcc, s63, v2
	v_mov_b32_e32 v2, 0xfffffd00
	v_mov_b32_e32 v3, 0xfffffe80
	v_cndmask_b32_e32 v2, v2, v3, vcc
	v_cmp_lt_i32_e64 s[0:1], s61, v1
	v_mov_b32_e32 v3, s15
	v_mov_b32_e32 v4, s16
	v_cmp_gt_i32_e64 s[2:3], s62, v1
	v_cndmask_b32_e64 v2, 0, v2, s[0:1]
	s_nop 0
	v_cndmask_b32_e64 v3, v3, v4, s[2:3]
	v_add3_u32 v4, v2, v1, v3
	v_mov_b32_e32 v2, v0
	v_mov_b32_e32 v3, v0
	v_mov_b32_e32 v1, v0
	v_mov_b64_e32 v[106:107], v[2:3]
	v_cmp_lt_i32_e64 s[2:3], -1, v4
	v_mov_b64_e32 v[104:105], v[0:1]
	s_and_saveexec_b64 s[12:13], s[2:3]
	s_cbranch_execz .LBB0_702
	s_and_b64 s[2:3], s[4:5], exec
	s_cselect_b32 s17, 2, 4
	s_and_b64 s[2:3], s[6:7], exec
	v_cndmask_b32_e32 v12, 0, v229, vcc
	v_mov_b32_e32 v5, v0
	s_cselect_b32 s2, 0, s17
	v_cndmask_b32_e64 v12, v230, v12, s[0:1]
	v_readlane_b32 s0, v254, 27
	v_lshlrev_b64 v[4:5], s2, v[4:5]
	v_readlane_b32 s1, v254, 28
	v_lshl_add_u64 v[4:5], v[4:5], 0, s[10:11]
	v_add_u32_e32 v12, s14, v12
	v_lshlrev_b32_e32 v13, 3, v170
	v_mov_b64_e32 v[14:15], s[0:1]
	v_and_or_b32 v12, v13, 56, v12
	v_mad_u64_u32 v[14:15], s[0:1], v4, s82, v[14:15]
	v_mad_i32_i24 v15, v5, s82, v15
	v_ashrrev_i32_e32 v13, 31, v12
	v_lshl_add_u64 v[4:5], v[12:13], 1, v[14:15]
	global_load_dwordx4 v[104:107], v[4:5], off nt
.LBB0_702:
	s_or_b64 exec, exec, s[12:13]
	v_add_u32_e32 v4, 0x1600, v170
	v_ashrrev_i32_e32 v4, 3, v4
	v_add_u32_e32 v5, 0xfffffe80, v4
	v_cmp_gt_u32_e32 vcc, s63, v5
	v_mov_b32_e32 v5, 0xfffffd00
	v_mov_b32_e32 v12, 0xfffffe80
	v_cndmask_b32_e32 v5, v5, v12, vcc
	v_cmp_lt_i32_e64 s[0:1], s61, v4
	v_mov_b32_e32 v12, s15
	v_mov_b32_e32 v13, s16
	v_cmp_gt_i32_e64 s[2:3], s62, v4
	v_cndmask_b32_e64 v5, 0, v5, s[0:1]
	v_mov_b64_e32 v[110:111], v[2:3]
	v_cndmask_b32_e64 v12, v12, v13, s[2:3]
	v_add3_u32 v4, v5, v4, v12
	v_cmp_lt_i32_e64 s[2:3], -1, v4
	v_mov_b64_e32 v[108:109], v[0:1]
	s_and_saveexec_b64 s[12:13], s[2:3]
	s_cbranch_execz .LBB0_704
	s_and_b64 s[2:3], s[4:5], exec
	s_cselect_b32 s17, 2, 4
	s_and_b64 s[2:3], s[6:7], exec
	v_cndmask_b32_e32 v1, 0, v229, vcc
	v_mov_b32_e32 v5, v0
	s_cselect_b32 s2, 0, s17
	v_cndmask_b32_e64 v1, v230, v1, s[0:1]
	v_readlane_b32 s0, v254, 27
	v_lshlrev_b64 v[2:3], s2, v[4:5]
	v_readlane_b32 s1, v254, 28
	v_lshl_add_u64 v[2:3], v[2:3], 0, s[10:11]
	v_add_u32_e32 v1, s14, v1
	v_lshlrev_b32_e32 v4, 3, v170
	v_mov_b64_e32 v[12:13], s[0:1]
	v_and_or_b32 v4, v4, 56, v1
	v_mad_u64_u32 v[12:13], s[0:1], v2, s82, v[12:13]
	v_mad_i32_i24 v13, v3, s82, v13
	v_ashrrev_i32_e32 v5, 31, v4
	v_lshl_add_u64 v[2:3], v[4:5], 1, v[12:13]
	global_load_dwordx4 v[108:111], v[2:3], off nt
.LBB0_704:
	s_or_b64 exec, exec, s[12:13]
	v_add_u32_e32 v1, 0x1800, v170
	v_ashrrev_i32_e32 v1, 3, v1
	v_add_u32_e32 v2, 0xfffffe80, v1
	v_cmp_gt_u32_e32 vcc, s63, v2
	v_mov_b32_e32 v2, 0xfffffd00
	v_mov_b32_e32 v3, 0xfffffe80
	v_cndmask_b32_e32 v2, v2, v3, vcc
	v_cmp_lt_i32_e64 s[0:1], s61, v1
	v_mov_b32_e32 v3, s15
	v_mov_b32_e32 v4, s16
	v_cmp_gt_i32_e64 s[2:3], s62, v1
	v_cndmask_b32_e64 v2, 0, v2, s[0:1]
	s_nop 0
	v_cndmask_b32_e64 v3, v3, v4, s[2:3]
	v_add3_u32 v4, v2, v1, v3
	v_mov_b32_e32 v2, v0
	v_mov_b32_e32 v3, v0
	v_mov_b32_e32 v1, v0
	v_mov_b64_e32 v[114:115], v[2:3]
	v_cmp_lt_i32_e64 s[2:3], -1, v4
	v_mov_b64_e32 v[112:113], v[0:1]
	s_and_saveexec_b64 s[12:13], s[2:3]
	s_cbranch_execz .LBB0_706
	s_and_b64 s[2:3], s[4:5], exec
	s_cselect_b32 s17, 2, 4
	s_and_b64 s[2:3], s[6:7], exec
	v_cndmask_b32_e32 v12, 0, v229, vcc
	v_mov_b32_e32 v5, v0
	s_cselect_b32 s2, 0, s17
	v_cndmask_b32_e64 v12, v230, v12, s[0:1]
	v_readlane_b32 s0, v254, 27
	v_lshlrev_b64 v[4:5], s2, v[4:5]
	v_readlane_b32 s1, v254, 28
	v_lshl_add_u64 v[4:5], v[4:5], 0, s[10:11]
	v_add_u32_e32 v12, s14, v12
	v_lshlrev_b32_e32 v13, 3, v170
	v_mov_b64_e32 v[14:15], s[0:1]
	v_and_or_b32 v12, v13, 56, v12
	v_mad_u64_u32 v[14:15], s[0:1], v4, s82, v[14:15]
	v_mad_i32_i24 v15, v5, s82, v15
	v_ashrrev_i32_e32 v13, 31, v12
	v_lshl_add_u64 v[4:5], v[12:13], 1, v[14:15]
	global_load_dwordx4 v[112:115], v[4:5], off nt
.LBB0_706:
	s_or_b64 exec, exec, s[12:13]
	v_add_u32_e32 v4, 0x1a00, v170
	v_ashrrev_i32_e32 v4, 3, v4
	v_add_u32_e32 v5, 0xfffffe80, v4
	v_cmp_gt_u32_e32 vcc, s63, v5
	v_mov_b32_e32 v5, 0xfffffd00
	v_mov_b32_e32 v12, 0xfffffe80
	v_cndmask_b32_e32 v5, v5, v12, vcc
	v_cmp_lt_i32_e64 s[0:1], s61, v4
	v_mov_b32_e32 v12, s15
	v_mov_b32_e32 v13, s16
	v_cmp_gt_i32_e64 s[2:3], s62, v4
	v_cndmask_b32_e64 v5, 0, v5, s[0:1]
	v_mov_b64_e32 v[118:119], v[2:3]
	v_cndmask_b32_e64 v12, v12, v13, s[2:3]
	v_add3_u32 v4, v5, v4, v12
	v_cmp_lt_i32_e64 s[2:3], -1, v4
	v_mov_b64_e32 v[116:117], v[0:1]
	s_and_saveexec_b64 s[12:13], s[2:3]
	s_cbranch_execz .LBB0_708
	s_and_b64 s[2:3], s[4:5], exec
	s_cselect_b32 s17, 2, 4
	s_and_b64 s[2:3], s[6:7], exec
	v_cndmask_b32_e32 v1, 0, v229, vcc
	v_mov_b32_e32 v5, v0
	s_cselect_b32 s2, 0, s17
	v_cndmask_b32_e64 v1, v230, v1, s[0:1]
	v_readlane_b32 s0, v254, 27
	v_lshlrev_b64 v[2:3], s2, v[4:5]
	v_readlane_b32 s1, v254, 28
	v_lshl_add_u64 v[2:3], v[2:3], 0, s[10:11]
	v_add_u32_e32 v1, s14, v1
	v_lshlrev_b32_e32 v4, 3, v170
	v_mov_b64_e32 v[12:13], s[0:1]
	v_and_or_b32 v4, v4, 56, v1
	v_mad_u64_u32 v[12:13], s[0:1], v2, s82, v[12:13]
	v_mad_i32_i24 v13, v3, s82, v13
	v_ashrrev_i32_e32 v5, 31, v4
	v_lshl_add_u64 v[2:3], v[4:5], 1, v[12:13]
	global_load_dwordx4 v[116:119], v[2:3], off nt
.LBB0_708:
	s_or_b64 exec, exec, s[12:13]
	v_add_u32_e32 v1, 0x1c00, v170
	v_ashrrev_i32_e32 v1, 3, v1
	v_add_u32_e32 v2, 0xfffffe80, v1
	v_cmp_gt_u32_e32 vcc, s63, v2
	v_mov_b32_e32 v2, 0xfffffd00
	v_mov_b32_e32 v3, 0xfffffe80
	v_cndmask_b32_e32 v2, v2, v3, vcc
	v_cmp_lt_i32_e64 s[0:1], s61, v1
	v_mov_b32_e32 v3, s15
	v_mov_b32_e32 v4, s16
	v_cmp_gt_i32_e64 s[2:3], s62, v1
	v_cndmask_b32_e64 v2, 0, v2, s[0:1]
	s_nop 0
	v_cndmask_b32_e64 v3, v3, v4, s[2:3]
	v_add3_u32 v4, v2, v1, v3
	v_mov_b32_e32 v2, v0
	v_mov_b32_e32 v3, v0
	v_mov_b32_e32 v1, v0
	v_mov_b64_e32 v[122:123], v[2:3]
	v_cmp_lt_i32_e64 s[2:3], -1, v4
	v_mov_b64_e32 v[120:121], v[0:1]
	s_and_saveexec_b64 s[12:13], s[2:3]
	s_cbranch_execz .LBB0_710
	s_and_b64 s[2:3], s[4:5], exec
	s_cselect_b32 s17, 2, 4
	s_and_b64 s[2:3], s[6:7], exec
	v_cndmask_b32_e32 v1, 0, v229, vcc
	v_mov_b32_e32 v5, v0
	s_cselect_b32 s2, 0, s17
	v_cndmask_b32_e64 v1, v230, v1, s[0:1]
	v_readlane_b32 s0, v254, 27
	v_lshlrev_b64 v[2:3], s2, v[4:5]
	v_readlane_b32 s1, v254, 28
	v_lshl_add_u64 v[2:3], v[2:3], 0, s[10:11]
	v_add_u32_e32 v1, s14, v1
	v_lshlrev_b32_e32 v4, 3, v170
	v_mov_b64_e32 v[12:13], s[0:1]
	v_and_or_b32 v4, v4, 56, v1
	v_mad_u64_u32 v[12:13], s[0:1], v2, s82, v[12:13]
	v_mad_i32_i24 v13, v3, s82, v13
	v_ashrrev_i32_e32 v5, 31, v4
	v_lshl_add_u64 v[2:3], v[4:5], 1, v[12:13]
	global_load_dwordx4 v[120:123], v[2:3], off nt
.LBB0_710:
	s_or_b64 exec, exec, s[12:13]
	v_add_u32_e32 v1, 0x1e00, v170
	v_ashrrev_i32_e32 v1, 3, v1
	v_add_u32_e32 v2, 0xfffffe80, v1
	v_cmp_gt_u32_e32 vcc, s63, v2
	v_mov_b32_e32 v2, 0xfffffd00
	v_mov_b32_e32 v3, 0xfffffe80
	v_cndmask_b32_e32 v2, v2, v3, vcc
	v_cmp_lt_i32_e64 s[0:1], s61, v1
	v_mov_b32_e32 v3, s15
	v_mov_b32_e32 v4, s16
	v_cmp_gt_i32_e64 s[2:3], s62, v1
	v_cndmask_b32_e64 v2, 0, v2, s[0:1]
	v_mov_b32_e32 v127, 0
	v_cndmask_b32_e64 v3, v3, v4, s[2:3]
	v_add3_u32 v2, v2, v1, v3
	v_cmp_lt_i32_e64 s[2:3], -1, v2
	v_mov_b32_e32 v126, 0
	v_mov_b32_e32 v125, 0
	v_mov_b32_e32 v124, 0
	s_and_saveexec_b64 s[12:13], s[2:3]
	s_cbranch_execz .LBB0_712
	s_and_b64 s[2:3], s[4:5], exec
	s_cselect_b32 s15, 2, 4
	s_and_b64 s[2:3], s[6:7], exec
	v_cndmask_b32_e32 v1, 0, v229, vcc
	v_mov_b32_e32 v3, v0
	s_cselect_b32 s2, 0, s15
	v_cndmask_b32_e64 v1, v230, v1, s[0:1]
	v_readlane_b32 s0, v254, 27
	v_lshlrev_b64 v[2:3], s2, v[2:3]
	v_readlane_b32 s1, v254, 28
	v_lshl_add_u64 v[2:3], v[2:3], 0, s[10:11]
	v_add_u32_e32 v1, s14, v1
	v_lshlrev_b32_e32 v4, 3, v170
	v_mov_b64_e32 v[12:13], s[0:1]
	v_and_or_b32 v4, v4, 56, v1
	v_mad_u64_u32 v[12:13], s[0:1], v2, s82, v[12:13]
	v_mad_i32_i24 v13, v3, s82, v13
	v_ashrrev_i32_e32 v5, 31, v4
	v_lshl_add_u64 v[2:3], v[4:5], 1, v[12:13]
	global_load_dwordx4 v[124:127], v[2:3], off nt

.LBB0_716:
	s_add_i32 s77, s4, s83
	s_cmp_ge_i32 s77, s70
	s_cselect_b64 s[30:31], -1, 0
	s_and_b64 vcc, exec, s[30:31]
	s_waitcnt vmcnt(0)
	ds_write_b128 v199, v[68:71]
	ds_write_b128 v200, v[64:67]
	ds_write_b128 v201, v[72:75]
	ds_write_b128 v202, v[76:79]
	ds_write_b128 v203, v[80:83]
	ds_write_b128 v204, v[84:87]
	ds_write_b128 v205, v[88:91]
	ds_write_b128 v206, v[92:95]
	ds_write_b128 v207, v[96:99]
	ds_write_b128 v208, v[100:103]
	ds_write_b128 v209, v[104:107]
	ds_write_b128 v210, v[108:111]
	ds_write_b128 v211, v[112:115]
	ds_write_b128 v212, v[116:119]
	ds_write_b128 v213, v[120:123]
	ds_write_b128 v214, v[124:127]
	s_waitcnt lgkmcnt(0)
	s_barrier
	s_cbranch_vccnz .LBB0_750
	s_abs_i32 s1, s77
	s_mul_hi_u32 s2, s1, s72
	s_mul_i32 s3, s2, s41
	s_sub_i32 s1, s1, s3
	s_ashr_i32 s0, s77, 31
	s_add_i32 s3, s2, 1
	s_sub_i32 s5, s1, s41
	s_cmp_ge_u32 s1, s41
	s_cselect_b32 s2, s3, s2
	s_cselect_b32 s1, s5, s1
	s_add_i32 s3, s2, 1
	s_cmp_ge_u32 s1, s41
	s_cselect_b32 s1, s3, s2
	s_xor_b32 s1, s1, s0
	s_sub_i32 s1, s1, s0
	s_ashr_i32 s0, s1, 31
	s_lshr_b32 s0, s0, 28
	s_add_i32 s0, s1, s0
	s_ashr_i32 s2, s0, 4
	s_abs_i32 s5, s2
	s_mul_hi_u32 s6, s5, s73
	s_mul_i32 s7, s6, s40
	s_and_b32 s3, s0, 0x3fffff0
	s_sub_i32 s5, s5, s7
	s_sub_i32 s3, s1, s3
	s_ashr_i32 s0, s0, 31
	s_add_i32 s7, s6, 1
	s_sub_i32 s8, s5, s40
	s_cmp_ge_u32 s5, s40
	s_cselect_b32 s6, s7, s6
	s_cselect_b32 s5, s8, s5
	s_add_i32 s7, s6, 1
	s_cmp_ge_u32 s5, s40
	s_cselect_b32 s5, s7, s6
	s_xor_b32 s5, s5, s0
	s_mul_i32 s1, s74, s1
	s_add_i32 s6, s76, s75
	s_sub_i32 s0, s5, s0
	s_add_i32 s6, s6, s1
	s_mul_i32 s5, s0, s40
	s_add_i32 s7, s6, 0xffffff80
	s_sub_i32 s2, s2, s5
	s_ashr_i32 s1, s0, 31
	v_mov_b32_e32 v1, s6
	v_mov_b32_e32 v2, s7
	s_lshl_b64 s[0:1], s[0:1], 13
	s_ashr_i32 s5, s2, 31
	v_cndmask_b32_e64 v1, v1, v2, s[36:37]
	v_mov_b32_e32 v66, v0
	v_mov_b32_e32 v67, v0
	s_add_u32 s0, s0, s2
	v_add_u32_e32 v2, v149, v1
	v_mov_b32_e32 v64, v0
	v_mov_b32_e32 v65, v0
	v_mov_b64_e32 v[70:71], v[66:67]
	s_addc_u32 s1, s1, s5
	s_lshl_b32 s5, s3, 6
	v_cmp_lt_i32_e32 vcc, -1, v2
	v_mov_b64_e32 v[68:69], v[64:65]
	s_and_saveexec_b64 s[2:3], vcc
	s_cbranch_execz .LBB0_719
	v_mov_b32_e32 v3, v0
	v_readlane_b32 s8, v254, 27
	v_lshlrev_b64 v[2:3], s71, v[2:3]
	v_readlane_b32 s9, v254, 28
	v_lshl_add_u64 v[2:3], v[2:3], 0, s[0:1]
	v_add_u32_e32 v4, s5, v150
	v_mov_b64_e32 v[6:7], s[8:9]
	v_mad_u64_u32 v[6:7], s[8:9], v2, s82, v[6:7]
	v_mad_i32_i24 v7, v3, s82, v7
	v_ashrrev_i32_e32 v5, 31, v4
	v_lshl_add_u64 v[2:3], v[4:5], 1, v[6:7]
	global_load_dwordx4 v[68:71], v[2:3], off nt
.LBB0_719:
	s_or_b64 exec, exec, s[2:3]
	v_mov_b32_e32 v1, s6
	v_mov_b32_e32 v2, s7
	v_cndmask_b32_e64 v1, v1, v2, s[38:39]
	v_add_u32_e32 v2, v151, v1
	v_cmp_lt_i32_e32 vcc, -1, v2
	s_and_saveexec_b64 s[2:3], vcc
	s_cbranch_execz .LBB0_721
	v_mov_b32_e32 v3, v0
	v_readlane_b32 s8, v254, 27
	v_lshlrev_b64 v[2:3], s71, v[2:3]
	v_readlane_b32 s9, v254, 28
	v_lshl_add_u64 v[2:3], v[2:3], 0, s[0:1]
	v_add_u32_e32 v4, s5, v152
	v_mov_b64_e32 v[6:7], s[8:9]
	v_mad_u64_u32 v[6:7], s[8:9], v2, s82, v[6:7]
	v_mad_i32_i24 v7, v3, s82, v7
	v_ashrrev_i32_e32 v5, 31, v4
	v_lshl_add_u64 v[2:3], v[4:5], 1, v[6:7]
	global_load_dwordx4 v[64:67], v[2:3], off nt
.LBB0_721:
	s_or_b64 exec, exec, s[2:3]
	v_mov_b32_e32 v1, s6
	v_mov_b32_e32 v2, s7
	v_cndmask_b32_e64 v1, v1, v2, s[20:21]
	v_mov_b32_e32 v2, v0
	v_mov_b32_e32 v3, v0
	v_add_u32_e32 v4, v153, v1
	v_mov_b32_e32 v1, v0
	v_mov_b64_e32 v[74:75], v[2:3]
	v_cmp_lt_i32_e32 vcc, -1, v4
	v_mov_b64_e32 v[72:73], v[0:1]
	s_and_saveexec_b64 s[2:3], vcc
	s_cbranch_execz .LBB0_723
	v_mov_b32_e32 v5, v0
	v_readlane_b32 s8, v254, 27
	v_lshlrev_b64 v[4:5], s71, v[4:5]
	v_readlane_b32 s9, v254, 28
	v_lshl_add_u64 v[4:5], v[4:5], 0, s[0:1]
	v_add_u32_e32 v6, s5, v154
	v_mov_b64_e32 v[8:9], s[8:9]
	v_mad_u64_u32 v[8:9], s[8:9], v4, s82, v[8:9]
	v_mad_i32_i24 v9, v5, s82, v9
	v_ashrrev_i32_e32 v7, 31, v6
	v_lshl_add_u64 v[4:5], v[6:7], 1, v[8:9]
	global_load_dwordx4 v[72:75], v[4:5], off nt
.LBB0_723:
	s_or_b64 exec, exec, s[2:3]
	v_mov_b32_e32 v4, s6
	v_mov_b32_e32 v5, s7
	v_cndmask_b32_e64 v4, v4, v5, s[42:43]
	v_add_u32_e32 v4, v155, v4
	v_mov_b64_e32 v[78:79], v[2:3]
	v_cmp_lt_i32_e32 vcc, -1, v4
	v_mov_b64_e32 v[76:77], v[0:1]
	s_and_saveexec_b64 s[2:3], vcc
	s_cbranch_execz .LBB0_725
	v_mov_b32_e32 v5, v0
	v_readlane_b32 s8, v254, 27
	v_lshlrev_b64 v[2:3], s71, v[4:5]
	v_readlane_b32 s9, v254, 28
	v_lshl_add_u64 v[2:3], v[2:3], 0, s[0:1]
	v_add_u32_e32 v4, s5, v156
	v_mov_b64_e32 v[6:7], s[8:9]
	v_mad_u64_u32 v[6:7], s[8:9], v2, s82, v[6:7]
	v_mad_i32_i24 v7, v3, s82, v7
	v_ashrrev_i32_e32 v5, 31, v4
	v_lshl_add_u64 v[2:3], v[4:5], 1, v[6:7]
	global_load_dwordx4 v[76:79], v[2:3], off nt
.LBB0_725:
	s_or_b64 exec, exec, s[2:3]
	v_mov_b32_e32 v1, s6
	v_mov_b32_e32 v2, s7
	v_cndmask_b32_e64 v1, v1, v2, s[44:45]
	v_mov_b32_e32 v2, v0
	v_mov_b32_e32 v3, v0
	v_add_u32_e32 v4, v157, v1
	v_mov_b32_e32 v1, v0
	v_mov_b64_e32 v[82:83], v[2:3]
	v_cmp_lt_i32_e32 vcc, -1, v4
	v_mov_b64_e32 v[80:81], v[0:1]
	s_and_saveexec_b64 s[2:3], vcc
	s_cbranch_execz .LBB0_727
	v_mov_b32_e32 v5, v0
	v_readlane_b32 s8, v254, 27
	v_lshlrev_b64 v[4:5], s71, v[4:5]
	v_readlane_b32 s9, v254, 28
	v_lshl_add_u64 v[4:5], v[4:5], 0, s[0:1]
	v_add_u32_e32 v6, s5, v158
	v_mov_b64_e32 v[8:9], s[8:9]
	v_mad_u64_u32 v[8:9], s[8:9], v4, s82, v[8:9]
	v_mad_i32_i24 v9, v5, s82, v9
	v_ashrrev_i32_e32 v7, 31, v6
	v_lshl_add_u64 v[4:5], v[6:7], 1, v[8:9]
	global_load_dwordx4 v[80:83], v[4:5], off nt
.LBB0_727:
	s_or_b64 exec, exec, s[2:3]
	v_mov_b32_e32 v4, s6
	v_mov_b32_e32 v5, s7
	v_cndmask_b32_e64 v4, v4, v5, s[46:47]
	v_add_u32_e32 v4, v159, v4
	v_mov_b64_e32 v[86:87], v[2:3]
	v_cmp_lt_i32_e32 vcc, -1, v4
	v_mov_b64_e32 v[84:85], v[0:1]
	s_and_saveexec_b64 s[2:3], vcc
	s_cbranch_execz .LBB0_729
	v_mov_b32_e32 v5, v0
	v_readlane_b32 s8, v254, 27
	v_lshlrev_b64 v[2:3], s71, v[4:5]
	v_readlane_b32 s9, v254, 28
	v_lshl_add_u64 v[2:3], v[2:3], 0, s[0:1]
	v_add_u32_e32 v4, s5, v160
	v_mov_b64_e32 v[6:7], s[8:9]
	v_mad_u64_u32 v[6:7], s[8:9], v2, s82, v[6:7]
	v_mad_i32_i24 v7, v3, s82, v7
	v_ashrrev_i32_e32 v5, 31, v4
	v_lshl_add_u64 v[2:3], v[4:5], 1, v[6:7]
	global_load_dwordx4 v[84:87], v[2:3], off nt
.LBB0_729:
	s_or_b64 exec, exec, s[2:3]
	v_mov_b32_e32 v1, s6
	v_mov_b32_e32 v2, s7
	v_cndmask_b32_e64 v1, v1, v2, s[48:49]
	v_mov_b32_e32 v2, v0
	v_mov_b32_e32 v3, v0
	v_add_u32_e32 v4, v161, v1
	v_mov_b32_e32 v1, v0
	v_mov_b64_e32 v[90:91], v[2:3]
	v_cmp_lt_i32_e32 vcc, -1, v4
	v_mov_b64_e32 v[88:89], v[0:1]
	s_and_saveexec_b64 s[2:3], vcc
	s_cbranch_execz .LBB0_731
	v_mov_b32_e32 v5, v0
	v_readlane_b32 s8, v254, 27
	v_lshlrev_b64 v[4:5], s71, v[4:5]
	v_readlane_b32 s9, v254, 28
	v_lshl_add_u64 v[4:5], v[4:5], 0, s[0:1]
	v_add_u32_e32 v6, s5, v171
	v_mov_b64_e32 v[8:9], s[8:9]
	v_mad_u64_u32 v[8:9], s[8:9], v4, s82, v[8:9]
	v_mad_i32_i24 v9, v5, s82, v9
	v_ashrrev_i32_e32 v7, 31, v6
	v_lshl_add_u64 v[4:5], v[6:7], 1, v[8:9]
	global_load_dwordx4 v[88:91], v[4:5], off nt
.LBB0_731:
	s_or_b64 exec, exec, s[2:3]
	v_mov_b32_e32 v4, s6
	v_mov_b32_e32 v5, s7
	v_cndmask_b32_e64 v4, v4, v5, s[50:51]
	v_add_u32_e32 v4, v172, v4
	v_mov_b64_e32 v[94:95], v[2:3]
	v_cmp_lt_i32_e32 vcc, -1, v4
	v_mov_b64_e32 v[92:93], v[0:1]
	s_and_saveexec_b64 s[2:3], vcc
	s_cbranch_execz .LBB0_733
	v_mov_b32_e32 v5, v0
	v_readlane_b32 s8, v254, 27
	v_lshlrev_b64 v[2:3], s71, v[4:5]
	v_readlane_b32 s9, v254, 28
	v_lshl_add_u64 v[2:3], v[2:3], 0, s[0:1]
	v_add_u32_e32 v4, s5, v173
	v_mov_b64_e32 v[6:7], s[8:9]
	v_mad_u64_u32 v[6:7], s[8:9], v2, s82, v[6:7]
	v_mad_i32_i24 v7, v3, s82, v7
	v_ashrrev_i32_e32 v5, 31, v4
	v_lshl_add_u64 v[2:3], v[4:5], 1, v[6:7]
	global_load_dwordx4 v[92:95], v[2:3], off nt
.LBB0_733:
	s_or_b64 exec, exec, s[2:3]
	v_mov_b32_e32 v1, s6
	v_mov_b32_e32 v2, s7
	v_cndmask_b32_e64 v1, v1, v2, s[52:53]
	v_mov_b32_e32 v2, v0
	v_mov_b32_e32 v3, v0
	v_add_u32_e32 v4, v174, v1
	v_mov_b32_e32 v1, v0
	v_mov_b64_e32 v[98:99], v[2:3]
	v_cmp_lt_i32_e32 vcc, -1, v4
	v_mov_b64_e32 v[96:97], v[0:1]
	s_and_saveexec_b64 s[2:3], vcc
	s_cbranch_execz .LBB0_735
	v_mov_b32_e32 v5, v0
	v_readlane_b32 s8, v254, 27
	v_lshlrev_b64 v[4:5], s71, v[4:5]
	v_readlane_b32 s9, v254, 28
	v_lshl_add_u64 v[4:5], v[4:5], 0, s[0:1]
	v_add_u32_e32 v6, s5, v175
	v_mov_b64_e32 v[8:9], s[8:9]
	v_mad_u64_u32 v[8:9], s[8:9], v4, s82, v[8:9]
	v_mad_i32_i24 v9, v5, s82, v9
	v_ashrrev_i32_e32 v7, 31, v6
	v_lshl_add_u64 v[4:5], v[6:7], 1, v[8:9]
	global_load_dwordx4 v[96:99], v[4:5], off nt
.LBB0_735:
	s_or_b64 exec, exec, s[2:3]
	v_mov_b32_e32 v4, s6
	v_mov_b32_e32 v5, s7
	v_cndmask_b32_e64 v4, v4, v5, s[54:55]
	v_add_u32_e32 v4, v176, v4
	v_mov_b64_e32 v[102:103], v[2:3]
	v_cmp_lt_i32_e32 vcc, -1, v4
	v_mov_b64_e32 v[100:101], v[0:1]
	s_and_saveexec_b64 s[2:3], vcc
	s_cbranch_execz .LBB0_737
	v_mov_b32_e32 v5, v0
	v_readlane_b32 s8, v254, 27
	v_lshlrev_b64 v[2:3], s71, v[4:5]
	v_readlane_b32 s9, v254, 28
	v_lshl_add_u64 v[2:3], v[2:3], 0, s[0:1]
	v_add_u32_e32 v4, s5, v177
	v_mov_b64_e32 v[6:7], s[8:9]
	v_mad_u64_u32 v[6:7], s[8:9], v2, s82, v[6:7]
	v_mad_i32_i24 v7, v3, s82, v7
	v_ashrrev_i32_e32 v5, 31, v4
	v_lshl_add_u64 v[2:3], v[4:5], 1, v[6:7]
	global_load_dwordx4 v[100:103], v[2:3], off nt
.LBB0_737:
	s_or_b64 exec, exec, s[2:3]
	v_mov_b32_e32 v1, s6
	v_mov_b32_e32 v2, s7
	v_cndmask_b32_e64 v1, v1, v2, s[56:57]
	v_mov_b32_e32 v2, v0
	v_mov_b32_e32 v3, v0
	v_add_u32_e32 v4, v178, v1
	v_mov_b32_e32 v1, v0
	v_mov_b64_e32 v[106:107], v[2:3]
	v_cmp_lt_i32_e32 vcc, -1, v4
	v_mov_b64_e32 v[104:105], v[0:1]
	s_and_saveexec_b64 s[2:3], vcc
	s_cbranch_execz .LBB0_739
	v_mov_b32_e32 v5, v0
	v_readlane_b32 s8, v254, 27
	v_lshlrev_b64 v[4:5], s71, v[4:5]
	v_readlane_b32 s9, v254, 28
	v_lshl_add_u64 v[4:5], v[4:5], 0, s[0:1]
	v_add_u32_e32 v6, s5, v179
	v_mov_b64_e32 v[8:9], s[8:9]
	v_mad_u64_u32 v[8:9], s[8:9], v4, s82, v[8:9]
	v_mad_i32_i24 v9, v5, s82, v9
	v_ashrrev_i32_e32 v7, 31, v6
	v_lshl_add_u64 v[4:5], v[6:7], 1, v[8:9]
	global_load_dwordx4 v[104:107], v[4:5], off nt
.LBB0_739:
	s_or_b64 exec, exec, s[2:3]
	v_mov_b32_e32 v4, s6
	v_mov_b32_e32 v5, s7
	v_cndmask_b32_e64 v4, v4, v5, s[58:59]
	v_add_u32_e32 v4, v180, v4
	v_mov_b64_e32 v[110:111], v[2:3]
	v_cmp_lt_i32_e32 vcc, -1, v4
	v_mov_b64_e32 v[108:109], v[0:1]
	s_and_saveexec_b64 s[2:3], vcc
	s_cbranch_execz .LBB0_741
	v_mov_b32_e32 v5, v0
	v_readlane_b32 s8, v254, 27
	v_lshlrev_b64 v[2:3], s71, v[4:5]
	v_readlane_b32 s9, v254, 28
	v_lshl_add_u64 v[2:3], v[2:3], 0, s[0:1]
	v_add_u32_e32 v4, s5, v181
	v_mov_b64_e32 v[6:7], s[8:9]
	v_mad_u64_u32 v[6:7], s[8:9], v2, s82, v[6:7]
	v_mad_i32_i24 v7, v3, s82, v7
	v_ashrrev_i32_e32 v5, 31, v4
	v_lshl_add_u64 v[2:3], v[4:5], 1, v[6:7]
	global_load_dwordx4 v[108:111], v[2:3], off nt
.LBB0_741:
	s_or_b64 exec, exec, s[2:3]
	v_mov_b32_e32 v1, s6
	v_mov_b32_e32 v2, s7
	v_cndmask_b32_e64 v1, v1, v2, s[60:61]
	v_mov_b32_e32 v2, v0
	v_mov_b32_e32 v3, v0
	v_add_u32_e32 v4, v182, v1
	v_mov_b32_e32 v1, v0
	v_mov_b64_e32 v[114:115], v[2:3]
	v_cmp_lt_i32_e32 vcc, -1, v4
	v_mov_b64_e32 v[112:113], v[0:1]
	s_and_saveexec_b64 s[2:3], vcc
	s_cbranch_execz .LBB0_743
	v_mov_b32_e32 v5, v0
	v_readlane_b32 s8, v254, 27
	v_lshlrev_b64 v[4:5], s71, v[4:5]
	v_readlane_b32 s9, v254, 28
	v_lshl_add_u64 v[4:5], v[4:5], 0, s[0:1]
	v_add_u32_e32 v6, s5, v183
	v_mov_b64_e32 v[8:9], s[8:9]
	v_mad_u64_u32 v[8:9], s[8:9], v4, s82, v[8:9]
	v_mad_i32_i24 v9, v5, s82, v9
	v_ashrrev_i32_e32 v7, 31, v6
	v_lshl_add_u64 v[4:5], v[6:7], 1, v[8:9]
	global_load_dwordx4 v[112:115], v[4:5], off nt
.LBB0_743:
	s_or_b64 exec, exec, s[2:3]
	v_mov_b32_e32 v4, s6
	v_mov_b32_e32 v5, s7
	v_cndmask_b32_e64 v4, v4, v5, s[62:63]
	v_add_u32_e32 v4, v184, v4
	v_mov_b64_e32 v[118:119], v[2:3]
	v_cmp_lt_i32_e32 vcc, -1, v4
	v_mov_b64_e32 v[116:117], v[0:1]
	s_and_saveexec_b64 s[2:3], vcc
	s_cbranch_execz .LBB0_745
	v_mov_b32_e32 v5, v0
	v_readlane_b32 s8, v254, 27
	v_lshlrev_b64 v[2:3], s71, v[4:5]
	v_readlane_b32 s9, v254, 28
	v_lshl_add_u64 v[2:3], v[2:3], 0, s[0:1]
	v_add_u32_e32 v4, s5, v185
	v_mov_b64_e32 v[6:7], s[8:9]
	v_mad_u64_u32 v[6:7], s[8:9], v2, s82, v[6:7]
	v_mad_i32_i24 v7, v3, s82, v7
	v_ashrrev_i32_e32 v5, 31, v4
	v_lshl_add_u64 v[2:3], v[4:5], 1, v[6:7]
	global_load_dwordx4 v[116:119], v[2:3], off nt
.LBB0_745:
	s_or_b64 exec, exec, s[2:3]
	v_mov_b32_e32 v1, s6
	v_mov_b32_e32 v2, s7
	v_cndmask_b32_e64 v1, v1, v2, s[64:65]
	v_mov_b32_e32 v2, v0
	v_mov_b32_e32 v3, v0
	v_add_u32_e32 v4, v186, v1
	v_mov_b32_e32 v1, v0
	v_mov_b64_e32 v[122:123], v[2:3]
	v_cmp_lt_i32_e32 vcc, -1, v4
	v_mov_b64_e32 v[120:121], v[0:1]
	s_and_saveexec_b64 s[2:3], vcc
	s_cbranch_execz .LBB0_747
	v_mov_b32_e32 v5, v0
	v_readlane_b32 s8, v254, 27
	v_lshlrev_b64 v[2:3], s71, v[4:5]
	v_readlane_b32 s9, v254, 28
	v_lshl_add_u64 v[2:3], v[2:3], 0, s[0:1]
	v_add_u32_e32 v4, s5, v187
	v_mov_b64_e32 v[6:7], s[8:9]
	v_mad_u64_u32 v[6:7], s[8:9], v2, s82, v[6:7]
	v_mad_i32_i24 v7, v3, s82, v7
	v_ashrrev_i32_e32 v5, 31, v4
	v_lshl_add_u64 v[2:3], v[4:5], 1, v[6:7]
	global_load_dwordx4 v[120:123], v[2:3], off nt
.LBB0_747:
	s_or_b64 exec, exec, s[2:3]
	v_mov_b32_e32 v1, s6
	v_mov_b32_e32 v2, s7
	v_cndmask_b32_e64 v1, v1, v2, s[66:67]
	v_add_u32_e32 v2, v188, v1
	v_cmp_lt_i32_e32 vcc, -1, v2
	v_mov_b32_e32 v127, 0
	v_mov_b32_e32 v126, 0
	v_mov_b32_e32 v125, 0
	v_mov_b32_e32 v124, 0
	s_and_saveexec_b64 s[2:3], vcc
	s_cbranch_execz .LBB0_749
	v_mov_b32_e32 v3, v0
	v_lshlrev_b64 v[2:3], s71, v[2:3]
	v_lshl_add_u64 v[2:3], v[2:3], 0, s[0:1]
	v_readlane_b32 s0, v254, 27
	v_readlane_b32 s1, v254, 28
	v_add_u32_e32 v4, s5, v189
	v_ashrrev_i32_e32 v5, 31, v4
	v_mov_b64_e32 v[6:7], s[0:1]
	v_mad_u64_u32 v[6:7], s[0:1], v2, s82, v[6:7]
	v_mad_i32_i24 v7, v3, s82, v7
	v_lshl_add_u64 v[2:3], v[4:5], 1, v[6:7]
	global_load_dwordx4 v[124:127], v[2:3], off nt
